# hazard-pad audit: removed hipcc s_nop pads after packed-f32 ops in GLA/GDN scan loops (no ISA hazard; LLVM VOP3P dst-sel false positive)
# speedup vs baseline: 1.0022x; 1.0022x over previous
; #define LBAR() do { asm volatile("s_waitcnt lgkmcnt(0)" ::: "memory"); __builtin_amdgcn_s_barrier(); asm volatile("" ::: "memory"); } while (0)
; #define LAS __attribute__((address_space(3)))
; #define GL_LDV(V, j_) do { \
;     V.f0 = L128(bq, (j_) * GL_VB); V.f1 = L128(bq, (j_) * GL_VB + 16); V.k0 = L128(bq, (j_) * GL_VB + 256); V.k1 = L128(bq, (j_) * GL_VB + 272); \
;     V.q0 = L128(bq, (j_) * GL_VB + 512); V.q1 = L128(bq, (j_) * GL_VB + 528); V.vv = L32(bv, (j_) * GL_VB + GL_OFF_V); V.kq = L32(bc, (j_) * GL_VB + GL_OFF_S); } while (0)
; #define GL_PIN(V) asm volatile("" : "+v"(V.f0), "+v"(V.f1), "+v"(V.k0), "+v"(V.k1), "+v"(V.q0), "+v"(V.q1), "+v"(V.vv), "+v"(V.kq), "+v"(S2[0]), "+v"(S2[1]), "+v"(S2[2]), "+v"(S2[3]))
; #define GL_2(jA, jB) GL_LDV(B, jA + 1); __builtin_amdgcn_sched_barrier(0); GL_STEP(A, jA); GL_PIN(B); \
;                      GL_LDV(A, jB + 1); __builtin_amdgcn_sched_barrier(0); GL_STEP(B, jB); GL_PIN(A);
; template <int NW>
; __device__ void scan_gla(const P& p, int l, int b, int h, int dir, int part, LAS char* lds) {
;     ...
;   gl_load<TPW, NCOL>(p, b, ch, vch, lane, dir, 0, wv, R);
;   GL_PREP(0);
;   gl_load<TPW, NCOL>(p, b, ch, vch, lane, dir, 1, wv, R);
;   LBAR();
;   for (int g = 0; g < NCHK; ++g) {
;     LAS char* vbuf = lds + (g & 1) * TC * GL_VB;
;     LAS float* obuf = (LAS float*)(lds + GL_OFF_Y + (g & 1) * TC * NCOL * 4);
;     {
;       GlVec A, B;
;       LAS char* bq = vbuf + dq * 32; LAS char* bv = vbuf + col * 4; LAS char* bc = vbuf;
;       GL_LDV(A, 0); GL_PIN(A);
; #pragma unroll 1
;       for (int s8 = 0; s8 < TC; s8 += 8) {
;         float ykeep = 0.f;
;         GL_2(0, 1) GL_2(2, 3) GL_2(4, 5) GL_2(6, 7)
;         obuf[(s8 + dq) * NCOL + col] = ykeep;
;         bq += 8 * GL_VB; bv += 8 * GL_VB; bc += 8 * GL_VB;
;       }
.LBB0_171:
	v_add_u32_e32 v92, 0x15400, v89
	v_add_u32_e32 v93, 0x15400, v90
	v_add_u32_e32 v94, 0x15400, v88
	ds_read_b32 v121, v94 offset:1808
	ds_read_b32 v120, v93 offset:1680
	ds_read_b128 v[96:99], v92 offset:1440
	ds_read_b128 v[100:103], v92 offset:1424
	ds_read_b128 v[104:107], v92 offset:1184
	ds_read_b128 v[108:111], v92 offset:1168
	ds_read_b128 v[112:115], v92 offset:928
	ds_read_b128 v[116:119], v92 offset:912
	v_pk_mul_f32 v[22:23], v[22:23], v[30:31]
	v_pk_mul_f32 v[4:5], v[4:5], v[32:33]
	v_pk_fma_f32 v[20:21], v[20:21], v[28:29], v[22:23]
	v_pk_fma_f32 v[12:13], v[12:13], v[32:33], v[20:21]
	v_pk_fma_f32 v[32:33], v[0:1], v[36:37], v[4:5] op_sel_hi:[1,0,1]
	v_pk_fma_f32 v[12:13], v[14:15], v[34:35], v[12:13]
	v_pk_mul_f32 v[0:1], v[6:7], v[34:35]
	v_pk_mul_f32 v[14:15], v[16:17], v[28:29]
	v_pk_fma_f32 v[34:35], v[2:3], v[36:37], v[0:1] op_sel_hi:[1,0,1]
	v_add_f32_e32 v0, v12, v13
	v_pk_fma_f32 v[28:29], v[8:9], v[36:37], v[14:15] op_sel_hi:[1,0,1]
	v_pk_mul_f32 v[8:9], v[18:19], v[30:31]
	v_add_f32_dpp v0, v0, v0 quad_perm:[1,0,3,2] row_mask:0xf bank_mask:0xf bound_ctrl:1
	v_pk_fma_f32 v[30:31], v[10:11], v[36:37], v[8:9] op_sel_hi:[1,0,1]
	s_nop 0
	v_add_f32_dpp v0, v0, v0 quad_perm:[2,3,0,1] row_mask:0xf bank_mask:0xf bound_ctrl:1
	s_nop 1
	v_add_f32_dpp v0, v0, v0 row_half_mirror row_mask:0xf bank_mask:0xf bound_ctrl:1
	v_fmac_f32_e32 v0, v36, v95
	v_cndmask_b32_e64 v95, 0, v0, s[42:43]
	s_waitcnt lgkmcnt(0)
	ds_read_b32 v122, v94 offset:2720
	ds_read_b32 v36, v93 offset:2592
	ds_read_b128 v[0:3], v92 offset:2352
	ds_read_b128 v[4:7], v92 offset:2336
	ds_read_b128 v[8:11], v92 offset:2096
	ds_read_b128 v[12:15], v92 offset:2080
	ds_read_b128 v[16:19], v92 offset:1840
	ds_read_b128 v[20:23], v92 offset:1824
	v_pk_mul_f32 v[102:103], v[30:31], v[102:103]
	v_pk_fma_f32 v[100:101], v[28:29], v[100:101], v[102:103]
	v_pk_fma_f32 v[96:97], v[32:33], v[96:97], v[100:101]
	v_pk_fma_f32 v[96:97], v[34:35], v[98:99], v[96:97]
	v_pk_mul_f32 v[98:99], v[108:109], v[120:121] op_sel_hi:[1,0]
	v_pk_fma_f32 v[116:117], v[28:29], v[116:117], v[98:99]
	v_pk_mul_f32 v[28:29], v[110:111], v[120:121] op_sel_hi:[1,0]
	v_pk_fma_f32 v[118:119], v[30:31], v[118:119], v[28:29]
	v_pk_mul_f32 v[28:29], v[104:105], v[120:121] op_sel_hi:[1,0]
	v_pk_fma_f32 v[112:113], v[32:33], v[112:113], v[28:29]
	v_pk_mul_f32 v[28:29], v[106:107], v[120:121] op_sel_hi:[1,0]
	v_pk_fma_f32 v[114:115], v[34:35], v[114:115], v[28:29]
	v_add_f32_e32 v28, v96, v97
	s_nop 1
	v_add_f32_dpp v28, v28, v28 quad_perm:[1,0,3,2] row_mask:0xf bank_mask:0xf bound_ctrl:1
	s_waitcnt lgkmcnt(0)
	s_nop 0
	v_add_f32_dpp v28, v28, v28 quad_perm:[2,3,0,1] row_mask:0xf bank_mask:0xf bound_ctrl:1
	s_nop 1
	v_add_f32_dpp v28, v28, v28 row_half_mirror row_mask:0xf bank_mask:0xf bound_ctrl:1
	v_fmac_f32_e32 v28, v120, v121
	v_cndmask_b32_e64 v95, v95, v28, s[44:45]
	ds_read_b32 v121, v94 offset:3632
	ds_read_b32 v120, v93 offset:3504
	ds_read_b128 v[28:31], v92 offset:3264
	ds_read_b128 v[32:35], v92 offset:3248
	ds_read_b128 v[96:99], v92 offset:3008
	ds_read_b128 v[100:103], v92 offset:2992
	ds_read_b128 v[104:107], v92 offset:2752
	ds_read_b128 v[108:111], v92 offset:2736
	v_pk_mul_f32 v[6:7], v[118:119], v[6:7]
	v_pk_fma_f32 v[4:5], v[116:117], v[4:5], v[6:7]
	v_pk_fma_f32 v[0:1], v[112:113], v[0:1], v[4:5]
	v_pk_fma_f32 v[0:1], v[114:115], v[2:3], v[0:1]
	v_pk_mul_f32 v[2:3], v[12:13], v[36:37] op_sel_hi:[1,0]
	v_add_f32_e32 v0, v0, v1
	v_pk_fma_f32 v[116:117], v[116:117], v[20:21], v[2:3]
	v_pk_mul_f32 v[2:3], v[14:15], v[36:37] op_sel_hi:[1,0]
	v_add_f32_dpp v0, v0, v0 quad_perm:[1,0,3,2] row_mask:0xf bank_mask:0xf bound_ctrl:1
	v_pk_fma_f32 v[118:119], v[118:119], v[22:23], v[2:3]
	v_pk_mul_f32 v[2:3], v[8:9], v[36:37] op_sel_hi:[1,0]
	v_add_f32_dpp v0, v0, v0 quad_perm:[2,3,0,1] row_mask:0xf bank_mask:0xf bound_ctrl:1
	v_pk_fma_f32 v[112:113], v[112:113], v[16:17], v[2:3]
	v_pk_mul_f32 v[2:3], v[10:11], v[36:37] op_sel_hi:[1,0]
	v_add_f32_dpp v0, v0, v0 row_half_mirror row_mask:0xf bank_mask:0xf bound_ctrl:1
	v_fmac_f32_e32 v0, v36, v122
	v_pk_fma_f32 v[114:115], v[114:115], v[18:19], v[2:3]
	v_cndmask_b32_e64 v95, v95, v0, s[46:47]
	s_waitcnt lgkmcnt(0)
	ds_read_b32 v122, v94 offset:4544
	ds_read_b32 v36, v93 offset:4416
	ds_read_b128 v[0:3], v92 offset:4176
	ds_read_b128 v[4:7], v92 offset:4160
	ds_read_b128 v[8:11], v92 offset:3920
	ds_read_b128 v[12:15], v92 offset:3904
	ds_read_b128 v[16:19], v92 offset:3664
	ds_read_b128 v[20:23], v92 offset:3648
	v_pk_mul_f32 v[34:35], v[118:119], v[34:35]
	v_pk_fma_f32 v[32:33], v[116:117], v[32:33], v[34:35]
	v_pk_fma_f32 v[28:29], v[112:113], v[28:29], v[32:33]
	v_pk_fma_f32 v[28:29], v[114:115], v[30:31], v[28:29]
	v_pk_mul_f32 v[30:31], v[100:101], v[120:121] op_sel_hi:[1,0]
	v_add_f32_e32 v28, v28, v29
	v_pk_fma_f32 v[116:117], v[116:117], v[108:109], v[30:31]
	v_pk_mul_f32 v[30:31], v[102:103], v[120:121] op_sel_hi:[1,0]
	v_add_f32_dpp v28, v28, v28 quad_perm:[1,0,3,2] row_mask:0xf bank_mask:0xf bound_ctrl:1
	v_pk_fma_f32 v[118:119], v[118:119], v[110:111], v[30:31]
	v_pk_mul_f32 v[30:31], v[96:97], v[120:121] op_sel_hi:[1,0]
	v_add_f32_dpp v28, v28, v28 quad_perm:[2,3,0,1] row_mask:0xf bank_mask:0xf bound_ctrl:1
	v_pk_fma_f32 v[112:113], v[112:113], v[104:105], v[30:31]
	v_pk_mul_f32 v[30:31], v[98:99], v[120:121] op_sel_hi:[1,0]
	v_add_f32_dpp v28, v28, v28 row_half_mirror row_mask:0xf bank_mask:0xf bound_ctrl:1
	v_fmac_f32_e32 v28, v120, v121
	v_pk_fma_f32 v[114:115], v[114:115], v[106:107], v[30:31]
	v_cndmask_b32_e64 v95, v95, v28, s[48:49]
	s_waitcnt lgkmcnt(0)
; #define LBAR() do { asm volatile("s_waitcnt lgkmcnt(0)" ::: "memory"); __builtin_amdgcn_s_barrier(); asm volatile("" ::: "memory"); } while (0)
; #define LAS __attribute__((address_space(3)))
; #define GL_LDV(V, j_) do { \
;     V.f0 = L128(bq, (j_) * GL_VB); V.f1 = L128(bq, (j_) * GL_VB + 16); V.k0 = L128(bq, (j_) * GL_VB + 256); V.k1 = L128(bq, (j_) * GL_VB + 272); \
;     V.q0 = L128(bq, (j_) * GL_VB + 512); V.q1 = L128(bq, (j_) * GL_VB + 528); V.vv = L32(bv, (j_) * GL_VB + GL_OFF_V); V.kq = L32(bc, (j_) * GL_VB + GL_OFF_S); } while (0)
; #define GL_PIN(V) asm volatile("" : "+v"(V.f0), "+v"(V.f1), "+v"(V.k0), "+v"(V.k1), "+v"(V.q0), "+v"(V.q1), "+v"(V.vv), "+v"(V.kq), "+v"(S2[0]), "+v"(S2[1]), "+v"(S2[2]), "+v"(S2[3]))
; #define GL_2(jA, jB) GL_LDV(B, jA + 1); __builtin_amdgcn_sched_barrier(0); GL_STEP(A, jA); GL_PIN(B); \
;                      GL_LDV(A, jB + 1); __builtin_amdgcn_sched_barrier(0); GL_STEP(B, jB); GL_PIN(A);
; template <int NW>
; __device__ void scan_gla(const P& p, int l, int b, int h, int dir, int part, LAS char* lds) {
;     ...
;   gl_load<TPW, NCOL>(p, b, ch, vch, lane, dir, 0, wv, R);
;   GL_PREP(0);
;   gl_load<TPW, NCOL>(p, b, ch, vch, lane, dir, 1, wv, R);
;   LBAR();
;   for (int g = 0; g < NCHK; ++g) {
;     LAS char* vbuf = lds + (g & 1) * TC * GL_VB;
;     LAS float* obuf = (LAS float*)(lds + GL_OFF_Y + (g & 1) * TC * NCOL * 4);
;     {
;       GlVec A, B;
;       LAS char* bq = vbuf + dq * 32; LAS char* bv = vbuf + col * 4; LAS char* bc = vbuf;
;       GL_LDV(A, 0); GL_PIN(A);
; #pragma unroll 1
;       for (int s8 = 0; s8 < TC; s8 += 8) {
;         float ykeep = 0.f;
;         GL_2(0, 1) GL_2(2, 3) GL_2(4, 5) GL_2(6, 7)
;         obuf[(s8 + dq) * NCOL + col] = ykeep;
;         bq += 8 * GL_VB; bv += 8 * GL_VB; bc += 8 * GL_VB;
;       }
	ds_read_b32 v121, v94 offset:5456
	ds_read_b32 v120, v93 offset:5328
	ds_read_b128 v[28:31], v92 offset:5088
	ds_read_b128 v[32:35], v92 offset:5072
	ds_read_b128 v[96:99], v92 offset:4832
	ds_read_b128 v[100:103], v92 offset:4816
	ds_read_b128 v[104:107], v92 offset:4576
	ds_read_b128 v[108:111], v92 offset:4560
	v_pk_mul_f32 v[6:7], v[118:119], v[6:7]
	v_pk_fma_f32 v[4:5], v[116:117], v[4:5], v[6:7]
	v_pk_fma_f32 v[0:1], v[112:113], v[0:1], v[4:5]
	v_pk_fma_f32 v[0:1], v[114:115], v[2:3], v[0:1]
	v_pk_mul_f32 v[2:3], v[12:13], v[36:37] op_sel_hi:[1,0]
	v_add_f32_e32 v0, v0, v1
	v_pk_fma_f32 v[116:117], v[116:117], v[20:21], v[2:3]
	v_pk_mul_f32 v[2:3], v[14:15], v[36:37] op_sel_hi:[1,0]
	v_add_f32_dpp v0, v0, v0 quad_perm:[1,0,3,2] row_mask:0xf bank_mask:0xf bound_ctrl:1
	v_pk_fma_f32 v[118:119], v[118:119], v[22:23], v[2:3]
	v_pk_mul_f32 v[2:3], v[8:9], v[36:37] op_sel_hi:[1,0]
	v_add_f32_dpp v0, v0, v0 quad_perm:[2,3,0,1] row_mask:0xf bank_mask:0xf bound_ctrl:1
	v_pk_fma_f32 v[112:113], v[112:113], v[16:17], v[2:3]
	v_pk_mul_f32 v[2:3], v[10:11], v[36:37] op_sel_hi:[1,0]
	v_add_f32_dpp v0, v0, v0 row_half_mirror row_mask:0xf bank_mask:0xf bound_ctrl:1
	v_fmac_f32_e32 v0, v36, v122
	v_pk_fma_f32 v[114:115], v[114:115], v[18:19], v[2:3]
	v_cndmask_b32_e64 v36, v95, v0, s[50:51]
	s_waitcnt lgkmcnt(0)
	ds_read_b32 v123, v94 offset:6368
	ds_read_b32 v122, v93 offset:6240
	ds_read_b128 v[0:3], v92 offset:6000
	ds_read_b128 v[4:7], v92 offset:5984
	ds_read_b128 v[8:11], v92 offset:5744
	ds_read_b128 v[12:15], v92 offset:5728
	ds_read_b128 v[16:19], v92 offset:5488
	ds_read_b128 v[20:23], v92 offset:5472
	v_pk_mul_f32 v[34:35], v[118:119], v[34:35]
	v_pk_fma_f32 v[32:33], v[116:117], v[32:33], v[34:35]
	v_pk_fma_f32 v[28:29], v[112:113], v[28:29], v[32:33]
	v_pk_fma_f32 v[28:29], v[114:115], v[30:31], v[28:29]
	v_pk_mul_f32 v[30:31], v[100:101], v[120:121] op_sel_hi:[1,0]
	v_add_f32_e32 v28, v28, v29
	v_pk_fma_f32 v[116:117], v[116:117], v[108:109], v[30:31]
	v_pk_mul_f32 v[30:31], v[102:103], v[120:121] op_sel_hi:[1,0]
	v_add_f32_dpp v28, v28, v28 quad_perm:[1,0,3,2] row_mask:0xf bank_mask:0xf bound_ctrl:1
	v_pk_fma_f32 v[118:119], v[118:119], v[110:111], v[30:31]
	v_pk_mul_f32 v[30:31], v[96:97], v[120:121] op_sel_hi:[1,0]
	v_add_f32_dpp v28, v28, v28 quad_perm:[2,3,0,1] row_mask:0xf bank_mask:0xf bound_ctrl:1
	v_pk_fma_f32 v[112:113], v[112:113], v[104:105], v[30:31]
	v_pk_mul_f32 v[30:31], v[98:99], v[120:121] op_sel_hi:[1,0]
	v_add_f32_dpp v28, v28, v28 row_half_mirror row_mask:0xf bank_mask:0xf bound_ctrl:1
	v_fmac_f32_e32 v28, v120, v121
	v_pk_fma_f32 v[114:115], v[114:115], v[106:107], v[30:31]
	v_cndmask_b32_e64 v121, v36, v28, s[52:53]
	s_waitcnt lgkmcnt(0)
	ds_read_b32 v124, v94 offset:7280
	ds_read_b32 v120, v93 offset:7152
	ds_read_b128 v[28:31], v92 offset:6912
	ds_read_b128 v[32:35], v92 offset:6896
	ds_read_b128 v[96:99], v92 offset:6656
	ds_read_b128 v[100:103], v92 offset:6640
	ds_read_b128 v[104:107], v92 offset:6400
	ds_read_b128 v[108:111], v92 offset:6384
	v_pk_mul_f32 v[6:7], v[118:119], v[6:7]
	v_pk_fma_f32 v[4:5], v[116:117], v[4:5], v[6:7]
	v_pk_fma_f32 v[0:1], v[112:113], v[0:1], v[4:5]
	v_pk_fma_f32 v[0:1], v[114:115], v[2:3], v[0:1]
	v_pk_mul_f32 v[2:3], v[12:13], v[122:123] op_sel_hi:[1,0]
	v_add_f32_e32 v0, v0, v1
	v_pk_fma_f32 v[116:117], v[116:117], v[20:21], v[2:3]
	v_pk_mul_f32 v[2:3], v[14:15], v[122:123] op_sel_hi:[1,0]
	v_add_f32_dpp v125, v0, v0 quad_perm:[1,0,3,2] row_mask:0xf bank_mask:0xf bound_ctrl:1
	v_pk_fma_f32 v[118:119], v[118:119], v[22:23], v[2:3]
	v_pk_mul_f32 v[2:3], v[8:9], v[122:123] op_sel_hi:[1,0]
	v_pk_fma_f32 v[112:113], v[112:113], v[16:17], v[2:3]
	v_pk_mul_f32 v[2:3], v[10:11], v[122:123] op_sel_hi:[1,0]
	v_pk_fma_f32 v[114:115], v[114:115], v[18:19], v[2:3]
	s_waitcnt lgkmcnt(0)
	ds_read_b32 v95, v94 offset:8192
	ds_read_b32 v36, v93 offset:8064
	ds_read_b128 v[12:15], v92 offset:7824
	ds_read_b128 v[20:23], v92 offset:7808
	ds_read_b128 v[0:3], v92 offset:7568
	ds_read_b128 v[8:11], v92 offset:7552
	ds_read_b128 v[4:7], v92 offset:7312
	ds_read_b128 v[16:19], v92 offset:7296
	v_add_f32_dpp v92, v125, v125 quad_perm:[2,3,0,1] row_mask:0xf bank_mask:0xf bound_ctrl:1
	s_nop 1
	v_add_f32_dpp v92, v92, v92 row_half_mirror row_mask:0xf bank_mask:0xf bound_ctrl:1
	v_fmac_f32_e32 v92, v122, v123
	v_cndmask_b32_e64 v94, v121, v92, s[54:55]
	v_pk_mul_f32 v[34:35], v[118:119], v[34:35]
	s_add_i32 s30, s30, 8
	v_pk_fma_f32 v[32:33], v[116:117], v[32:33], v[34:35]
	v_pk_mul_f32 v[34:35], v[98:99], v[120:121] op_sel_hi:[1,0]
	v_pk_fma_f32 v[28:29], v[112:113], v[28:29], v[32:33]
	v_pk_mul_f32 v[32:33], v[96:97], v[120:121] op_sel_hi:[1,0]
	v_pk_fma_f32 v[92:93], v[114:115], v[30:31], v[28:29]
	v_pk_mul_f32 v[28:29], v[100:101], v[120:121] op_sel_hi:[1,0]
	v_add_f32_e32 v92, v92, v93
	v_pk_mul_f32 v[30:31], v[102:103], v[120:121] op_sel_hi:[1,0]
	v_pk_fma_f32 v[28:29], v[116:117], v[108:109], v[28:29]
	v_add_f32_dpp v92, v92, v92 quad_perm:[1,0,3,2] row_mask:0xf bank_mask:0xf bound_ctrl:1
	v_pk_fma_f32 v[30:31], v[118:119], v[110:111], v[30:31]
	v_pk_fma_f32 v[32:33], v[112:113], v[104:105], v[32:33]
	v_add_f32_dpp v92, v92, v92 quad_perm:[2,3,0,1] row_mask:0xf bank_mask:0xf bound_ctrl:1
	v_pk_fma_f32 v[34:35], v[114:115], v[106:107], v[34:35]
	v_add_u32_e32 v93, 0, v91
	v_add_f32_dpp v92, v92, v92 row_half_mirror row_mask:0xf bank_mask:0xf bound_ctrl:1
	v_fmac_f32_e32 v92, v120, v124
	v_cndmask_b32_e64 v92, v94, v92, s[56:57]
	v_add_u32_e32 v89, 0x1c80, v89
	v_add_u32_e32 v90, 0x1c80, v90
	v_add_u32_e32 v88, 0x1c80, v88
	v_add_u32_e32 v91, 0x400, v91
	s_cmp_gt_u32 s30, 23
	s_waitcnt lgkmcnt(0)
	ds_write_b32 v93, v92
	s_cbranch_scc0 .LBB0_171
	s_add_i32 s30, s27, 1
	s_cmpk_lg_i32 s27, 0x87
	s_cbranch_scc0 .LBB0_206
	s_lshl_b32 s20, s30, 5
	s_and_b32 s20, s20, 32
	s_mulk_i32 s20, 0x390
	s_waitcnt vmcnt(0)
	v_lshlrev_b32_e32 v0, 16, v42
	v_mul_f32_e32 v2, 0x3e000000, v0
	v_add_u32_e32 v0, s20, v41
	v_lshlrev_b32_e32 v3, 16, v43
	v_lshl_add_u32 v1, v37, 2, v0
	v_mul_f32_e32 v2, v45, v2
	ds_write2st64_b32 v1, v45, v3 offset1:1
	ds_write_b32 v1, v2 offset:512
	v_lshlrev_b32_e32 v2, 16, v47
	v_mul_f32_e32 v2, 0x3e000000, v2
	v_lshlrev_b32_e32 v3, 16, v48
	v_add_u32_e32 v4, 0x90, v1
	v_mul_f32_e32 v2, v50, v2
	ds_write2st64_b32 v4, v50, v3 offset0:3 offset1:4
	ds_write_b32 v1, v2 offset:1424
	v_lshlrev_b32_e32 v2, 16, v52
	v_mul_f32_e32 v2, 0x3e000000, v2
	v_lshlrev_b32_e32 v3, 16, v53
	v_add_u32_e32 v4, 32, v1
	v_mul_f32_e32 v2, v55, v2
	ds_write2st64_b32 v4, v55, v3 offset0:7 offset1:8
	ds_write_b32 v1, v2 offset:2336
	v_lshlrev_b32_e32 v2, 16, v59
	v_mul_f32_e32 v2, 0x3e000000, v2
	v_lshlrev_b32_e32 v3, 16, v61
	v_add_u32_e32 v4, 0xb0, v1
	v_mul_f32_e32 v2, v68, v2
	ds_write2st64_b32 v4, v68, v3 offset0:10 offset1:11
	ds_write_b32 v1, v2 offset:3248
	v_lshlrev_b32_e32 v2, 16, v70
	v_mul_f32_e32 v2, 0x3e000000, v2
	v_lshlrev_b32_e32 v3, 16, v71
	v_add_u32_e32 v4, 64, v1
	v_mul_f32_e32 v2, v73, v2
	ds_write2st64_b32 v4, v73, v3 offset0:14 offset1:15
	ds_write_b32 v1, v2 offset:4160
	v_lshlrev_b32_e32 v2, 16, v75
	v_mul_f32_e32 v2, 0x3e000000, v2
	v_lshlrev_b32_e32 v3, 16, v76
	v_add_u32_e32 v4, 0xd0, v1
	v_mul_f32_e32 v2, v78, v2
	ds_write2st64_b32 v4, v78, v3 offset0:17 offset1:18
	ds_write_b32 v1, v2 offset:5072
	v_lshlrev_b32_e32 v2, 16, v80
	v_mul_f32_e32 v2, 0x3e000000, v2
	v_lshlrev_b32_e32 v3, 16, v81
	v_add_u32_e32 v4, 0x60, v1
	v_mul_f32_e32 v2, v83, v2
	ds_write2st64_b32 v4, v83, v3 offset0:21 offset1:22
	ds_write_b32 v1, v2 offset:5984
	v_lshlrev_b32_e32 v2, 16, v25
	v_mul_f32_e32 v2, 0x3e000000, v2
	v_lshlrev_b32_e32 v3, 16, v85
	v_add_u32_e32 v4, 0xf0, v1
	v_mul_f32_e32 v2, v86, v2
	ds_write2st64_b32 v4, v86, v3 offset0:24 offset1:25
	ds_write_b32 v1, v2 offset:6896
	s_and_saveexec_b64 s[36:37], s[38:39]
	v_lshlrev_b32_e32 v2, 16, v44
	ds_write_b32 v1, v2 offset:768
	v_lshlrev_b32_e32 v2, 16, v49
	ds_write_b32 v1, v2 offset:1680
	v_lshlrev_b32_e32 v2, 16, v54
	ds_write_b32 v1, v2 offset:2592
	v_lshlrev_b32_e32 v2, 16, v65
	ds_write_b32 v1, v2 offset:3504
	v_lshlrev_b32_e32 v2, 16, v72
	ds_write_b32 v1, v2 offset:4416
	v_lshlrev_b32_e32 v2, 16, v77
	ds_write_b32 v1, v2 offset:5328
	v_lshlrev_b32_e32 v2, 16, v82
	ds_write_b32 v1, v2 offset:6240
	v_lshlrev_b32_e32 v2, 16, v27
	ds_write_b32 v1, v2 offset:7152
	s_or_b64 exec, exec, s[36:37]
	s_and_saveexec_b64 s[36:37], s[40:41]
	ds_write_b32 v0, v46 offset:896
	ds_write_b32 v0, v51 offset:1808
	ds_write_b32 v0, v56 offset:2720
	ds_write_b32 v0, v69 offset:3632
	ds_write_b32 v0, v74 offset:4544
	ds_write_b32 v0, v79 offset:5456
	ds_write_b32 v0, v84 offset:6368
	ds_write_b32 v0, v87 offset:7280
	s_or_b64 exec, exec, s[36:37]

.LBB0_245:
	v_add_u32_e32 v3, v128, v109
	v_add_u32_e32 v142, v128, v100
	ds_read_b128 v[144:147], v3 offset:592
	ds_read_b128 v[148:151], v3 offset:576
	ds_read_b128 v[152:155], v3 offset:560
	ds_read_b128 v[156:159], v3 offset:544
	ds_read_b128 v[160:163], v3
	ds_read_b128 v[164:167], v3 offset:16
	ds_read_b128 v[190:193], v3 offset:32
	ds_read_b128 v[194:197], v3 offset:48
	ds_read_b32 v143, v142 offset:1088
	ds_read_b128 v[198:201], v128 offset:1216
	v_pk_mul_f32 v[52:53], v[48:49], v[6:7]
	v_pk_mul_f32 v[34:35], v[48:49], v[34:35]
	v_pk_fma_f32 v[52:53], v[50:51], v[4:5], v[52:53]
	v_pk_fma_f32 v[32:33], v[50:51], v[32:33], v[34:35]
	v_pk_fma_f32 v[52:53], v[46:47], v[8:9], v[52:53]
	v_pk_fma_f32 v[28:29], v[46:47], v[28:29], v[32:33]
	v_pk_fma_f32 v[52:53], v[44:45], v[10:11], v[52:53]
	v_pk_fma_f32 v[28:29], v[44:45], v[30:31], v[28:29]
	v_pk_fma_f32 v[52:53], v[42:43], v[12:13], v[52:53]
	v_pk_fma_f32 v[24:25], v[42:43], v[24:25], v[28:29]
	v_pk_fma_f32 v[52:53], v[40:41], v[14:15], v[52:53]
	v_pk_fma_f32 v[24:25], v[40:41], v[26:27], v[24:25]
	v_pk_fma_f32 v[52:53], v[38:39], v[16:17], v[52:53]
	v_pk_fma_f32 v[20:21], v[38:39], v[20:21], v[24:25]
	v_pk_fma_f32 v[52:53], v[36:37], v[18:19], v[52:53]
	v_pk_fma_f32 v[20:21], v[36:37], v[22:23], v[20:21]
	v_add_f32_e32 v22, v52, v53
	v_add_f32_e32 v20, v20, v21
	v_rcp_f32_e32 v23, v0
	v_add_f32_dpp v22, v22, v22 quad_perm:[1,0,3,2] row_mask:0xf bank_mask:0xf bound_ctrl:1
	v_add_f32_dpp v20, v20, v20 quad_perm:[1,0,3,2] row_mask:0xf bank_mask:0xf bound_ctrl:1
	s_nop 0
	v_add_f32_dpp v22, v22, v22 quad_perm:[2,3,0,1] row_mask:0xf bank_mask:0xf bound_ctrl:1
	v_add_f32_dpp v20, v20, v20 quad_perm:[2,3,0,1] row_mask:0xf bank_mask:0xf bound_ctrl:1
	s_nop 0
	v_add_f32_dpp v22, v22, v22 row_half_mirror row_mask:0xf bank_mask:0xf bound_ctrl:1
	v_add_f32_dpp v20, v20, v20 row_half_mirror row_mask:0xf bank_mask:0xf bound_ctrl:1
	v_fma_f32 v21, -v0, v22, v55
	v_pk_mul_f32 v[52:53], v[0:1], v[20:21]
	v_mul_f32_e32 v20, v23, v53
	v_pk_fma_f32 v[50:51], v[4:5], v[20:21], v[50:51] op_sel_hi:[1,0,1]
	v_pk_fma_f32 v[48:49], v[6:7], v[20:21], v[48:49] op_sel_hi:[1,0,1]
	v_pk_fma_f32 v[46:47], v[8:9], v[20:21], v[46:47] op_sel_hi:[1,0,1]
	v_pk_fma_f32 v[44:45], v[10:11], v[20:21], v[44:45] op_sel_hi:[1,0,1]
	v_pk_fma_f32 v[42:43], v[12:13], v[20:21], v[42:43] op_sel_hi:[1,0,1]
	v_pk_fma_f32 v[40:41], v[14:15], v[20:21], v[40:41] op_sel_hi:[1,0,1]
	v_pk_fma_f32 v[54:55], v[16:17], v[20:21], v[38:39] op_sel_hi:[1,0,1]
	v_pk_fma_f32 v[202:203], v[18:19], v[20:21], v[36:37] op_sel_hi:[1,0,1]
	v_fmac_f32_e32 v52, v2, v53
	s_waitcnt lgkmcnt(0)
	ds_read_b128 v[4:7], v3 offset:1824
	ds_read_b128 v[8:11], v3 offset:1808
	ds_read_b128 v[12:15], v3 offset:1792
	ds_read_b128 v[16:19], v3 offset:1776
	ds_read_b128 v[20:23], v3 offset:1232
	ds_read_b128 v[24:27], v3 offset:1248
	ds_read_b128 v[28:31], v3 offset:1264
	ds_read_b128 v[32:35], v3 offset:1280
	ds_read_b32 v206, v142 offset:2320
	ds_read_b128 v[36:39], v128 offset:2448
	v_cndmask_b32_e64 v201, 0, v52, s[46:47]
	v_pk_mul_f32 v[158:159], v[48:49], v[158:159]
	v_pk_mul_f32 v[52:53], v[48:49], v[162:163]
	v_pk_fma_f32 v[156:157], v[50:51], v[156:157], v[158:159]
	v_pk_fma_f32 v[52:53], v[50:51], v[160:161], v[52:53]
	v_pk_fma_f32 v[152:153], v[46:47], v[152:153], v[156:157]
	v_pk_fma_f32 v[52:53], v[46:47], v[164:165], v[52:53]
	v_pk_fma_f32 v[152:153], v[44:45], v[154:155], v[152:153]
	v_pk_fma_f32 v[52:53], v[44:45], v[166:167], v[52:53]
	v_pk_fma_f32 v[148:149], v[42:43], v[148:149], v[152:153]
	v_pk_fma_f32 v[52:53], v[42:43], v[190:191], v[52:53]
	v_pk_fma_f32 v[148:149], v[40:41], v[150:151], v[148:149]
	v_pk_fma_f32 v[52:53], v[40:41], v[192:193], v[52:53]
	v_pk_fma_f32 v[144:145], v[54:55], v[144:145], v[148:149]
	v_pk_fma_f32 v[52:53], v[54:55], v[194:195], v[52:53]
	v_pk_fma_f32 v[144:145], v[202:203], v[146:147], v[144:145]
	v_pk_fma_f32 v[52:53], v[202:203], v[196:197], v[52:53]
	v_add_f32_e32 v2, v144, v145
	v_add_f32_e32 v1, v52, v53
	v_mul_f32_e32 v0, v0, v198
	v_add_f32_dpp v2, v2, v2 quad_perm:[1,0,3,2] row_mask:0xf bank_mask:0xf bound_ctrl:1
	v_add_f32_dpp v1, v1, v1 quad_perm:[1,0,3,2] row_mask:0xf bank_mask:0xf bound_ctrl:1
	v_mov_b32_e32 v53, v200
	v_add_f32_dpp v2, v2, v2 quad_perm:[2,3,0,1] row_mask:0xf bank_mask:0xf bound_ctrl:1
	v_add_f32_dpp v1, v1, v1 quad_perm:[2,3,0,1] row_mask:0xf bank_mask:0xf bound_ctrl:1
	s_nop 0
	v_add_f32_dpp v52, v2, v2 row_half_mirror row_mask:0xf bank_mask:0xf bound_ctrl:1
	v_rcp_f32_e32 v2, v0
	v_add_f32_dpp v1, v1, v1 row_half_mirror row_mask:0xf bank_mask:0xf bound_ctrl:1
	v_fma_f32 v1, -v0, v1, v143
	v_mul_f32_e32 v1, v199, v1
	v_mul_f32_e32 v2, v2, v1
	v_pk_fma_f32 v[198:199], v[160:161], v[2:3], v[50:51] op_sel_hi:[1,0,1]
	v_pk_fma_f32 v[204:205], v[162:163], v[2:3], v[48:49] op_sel_hi:[1,0,1]
	v_pk_fma_f32 v[164:165], v[164:165], v[2:3], v[46:47] op_sel_hi:[1,0,1]
	v_pk_fma_f32 v[166:167], v[166:167], v[2:3], v[44:45] op_sel_hi:[1,0,1]
	v_pk_fma_f32 v[190:191], v[190:191], v[2:3], v[42:43] op_sel_hi:[1,0,1]
	v_pk_fma_f32 v[192:193], v[192:193], v[2:3], v[40:41] op_sel_hi:[1,0,1]
	v_pk_fma_f32 v[194:195], v[194:195], v[2:3], v[54:55] op_sel_hi:[1,0,1]
	v_pk_fma_f32 v[196:197], v[196:197], v[2:3], v[202:203] op_sel_hi:[1,0,1]
	v_pk_mul_f32 v[40:41], v[52:53], v[0:1]
	s_waitcnt lgkmcnt(0)
	v_add_f32_e32 v1, v40, v41
	ds_read_b32 v143, v142 offset:3552
	ds_read_b128 v[40:43], v3 offset:3056
	ds_read_b128 v[44:47], v3 offset:3040
	ds_read_b128 v[48:51], v3 offset:3024
	ds_read_b128 v[52:55], v3 offset:3008
	ds_read_b128 v[144:147], v3 offset:2464
	ds_read_b128 v[148:151], v3 offset:2480
	ds_read_b128 v[152:155], v3 offset:2496
	ds_read_b128 v[156:159], v3 offset:2512
	ds_read_b128 v[160:163], v128 offset:3680
	v_cndmask_b32_e64 v2, v201, v1, s[48:49]
	v_pk_mul_f32 v[200:201], v[204:205], v[22:23]
	v_pk_mul_f32 v[18:19], v[204:205], v[18:19]
	v_pk_fma_f32 v[200:201], v[198:199], v[20:21], v[200:201]
	v_pk_fma_f32 v[16:17], v[198:199], v[16:17], v[18:19]
	v_pk_fma_f32 v[200:201], v[164:165], v[24:25], v[200:201]
	v_pk_fma_f32 v[12:13], v[164:165], v[12:13], v[16:17]
	v_pk_fma_f32 v[200:201], v[166:167], v[26:27], v[200:201]
	v_pk_fma_f32 v[12:13], v[166:167], v[14:15], v[12:13]
	v_pk_fma_f32 v[200:201], v[190:191], v[28:29], v[200:201]
	v_mul_f32_e32 v207, v0, v36
	v_pk_fma_f32 v[200:201], v[192:193], v[30:31], v[200:201]
	v_pk_fma_f32 v[8:9], v[190:191], v[8:9], v[12:13]
	v_pk_fma_f32 v[200:201], v[194:195], v[32:33], v[200:201]
	v_rcp_f32_e32 v0, v207
	v_pk_fma_f32 v[200:201], v[196:197], v[34:35], v[200:201]
	v_pk_fma_f32 v[8:9], v[192:193], v[10:11], v[8:9]
	v_add_f32_e32 v1, v200, v201
	v_pk_fma_f32 v[4:5], v[194:195], v[4:5], v[8:9]
	s_nop 0
	v_add_f32_dpp v1, v1, v1 quad_perm:[1,0,3,2] row_mask:0xf bank_mask:0xf bound_ctrl:1
	v_pk_fma_f32 v[4:5], v[196:197], v[6:7], v[4:5]
	s_nop 0
	v_add_f32_dpp v1, v1, v1 quad_perm:[2,3,0,1] row_mask:0xf bank_mask:0xf bound_ctrl:1
	v_add_f32_e32 v4, v4, v5
	s_nop 0
	v_add_f32_dpp v1, v1, v1 row_half_mirror row_mask:0xf bank_mask:0xf bound_ctrl:1
	v_fma_f32 v1, -v207, v1, v206
	v_mul_f32_e32 v206, v37, v1
	v_mul_f32_e32 v0, v0, v206
	v_add_f32_dpp v4, v4, v4 quad_perm:[1,0,3,2] row_mask:0xf bank_mask:0xf bound_ctrl:1
	v_pk_fma_f32 v[36:37], v[20:21], v[0:1], v[198:199] op_sel_hi:[1,0,1]
	v_pk_fma_f32 v[198:199], v[22:23], v[0:1], v[204:205] op_sel_hi:[1,0,1]
	v_pk_fma_f32 v[200:201], v[24:25], v[0:1], v[164:165] op_sel_hi:[1,0,1]
	v_pk_fma_f32 v[202:203], v[26:27], v[0:1], v[166:167] op_sel_hi:[1,0,1]
	v_pk_fma_f32 v[190:191], v[28:29], v[0:1], v[190:191] op_sel_hi:[1,0,1]
	v_pk_fma_f32 v[192:193], v[30:31], v[0:1], v[192:193] op_sel_hi:[1,0,1]
	v_pk_fma_f32 v[194:195], v[32:33], v[0:1], v[194:195] op_sel_hi:[1,0,1]
	v_pk_fma_f32 v[0:1], v[34:35], v[0:1], v[196:197] op_sel_hi:[1,0,1]
	v_add_f32_dpp v39, v4, v4 quad_perm:[2,3,0,1] row_mask:0xf bank_mask:0xf bound_ctrl:1
	s_waitcnt lgkmcnt(0)
	ds_read_b128 v[4:7], v3 offset:4288
	ds_read_b128 v[8:11], v3 offset:4272
	ds_read_b128 v[12:15], v3 offset:4256
	ds_read_b128 v[16:19], v3 offset:4240
	ds_read_b128 v[20:23], v3 offset:3696
	ds_read_b128 v[24:27], v3 offset:3712
	ds_read_b128 v[28:31], v3 offset:3728
	ds_read_b128 v[32:35], v3 offset:3744
	ds_read_b32 v204, v142 offset:4784
	ds_read_b128 v[164:167], v128 offset:4912
	v_add_f32_dpp v39, v39, v39 row_half_mirror row_mask:0xf bank_mask:0xf bound_ctrl:1
	v_mul_f32_e32 v38, v38, v206
	v_fmac_f32_e32 v38, v207, v39
	v_cndmask_b32_e64 v163, v2, v38, s[50:51]
	v_pk_mul_f32 v[38:39], v[198:199], v[146:147]
	v_pk_mul_f32 v[54:55], v[198:199], v[54:55]
	v_pk_fma_f32 v[38:39], v[36:37], v[144:145], v[38:39]
	v_pk_fma_f32 v[52:53], v[36:37], v[52:53], v[54:55]
	v_pk_fma_f32 v[38:39], v[200:201], v[148:149], v[38:39]
	v_pk_fma_f32 v[48:49], v[200:201], v[48:49], v[52:53]
	v_pk_fma_f32 v[38:39], v[202:203], v[150:151], v[38:39]
	v_pk_fma_f32 v[48:49], v[202:203], v[50:51], v[48:49]
	v_pk_fma_f32 v[38:39], v[190:191], v[152:153], v[38:39]
	v_pk_fma_f32 v[44:45], v[190:191], v[44:45], v[48:49]
	v_pk_fma_f32 v[38:39], v[192:193], v[154:155], v[38:39]
	v_pk_fma_f32 v[44:45], v[192:193], v[46:47], v[44:45]
	v_pk_fma_f32 v[38:39], v[194:195], v[156:157], v[38:39]
	v_pk_fma_f32 v[40:41], v[194:195], v[40:41], v[44:45]
	v_pk_fma_f32 v[38:39], v[0:1], v[158:159], v[38:39]
	v_pk_fma_f32 v[40:41], v[0:1], v[42:43], v[40:41]
	v_add_f32_e32 v2, v38, v39
	s_nop 1
	v_add_f32_dpp v2, v2, v2 quad_perm:[1,0,3,2] row_mask:0xf bank_mask:0xf bound_ctrl:1
	s_nop 1
	v_add_f32_dpp v2, v2, v2 quad_perm:[2,3,0,1] row_mask:0xf bank_mask:0xf bound_ctrl:1
	s_nop 1
	v_add_f32_dpp v38, v2, v2 row_half_mirror row_mask:0xf bank_mask:0xf bound_ctrl:1
	v_add_f32_e32 v2, v40, v41
	s_nop 1
	v_add_f32_dpp v39, v2, v2 quad_perm:[1,0,3,2] row_mask:0xf bank_mask:0xf bound_ctrl:1
	v_mul_f32_e32 v2, v207, v160
	v_rcp_f32_e32 v40, v2
	v_fma_f32 v38, -v2, v38, v143
	v_mul_f32_e32 v143, v161, v38
	v_add_f32_dpp v205, v39, v39 quad_perm:[2,3,0,1] row_mask:0xf bank_mask:0xf bound_ctrl:1
	v_mul_f32_e32 v38, v40, v143
	v_pk_fma_f32 v[36:37], v[144:145], v[38:39], v[36:37] op_sel_hi:[1,0,1]
	v_pk_fma_f32 v[40:41], v[146:147], v[38:39], v[198:199] op_sel_hi:[1,0,1]
	v_pk_fma_f32 v[42:43], v[148:149], v[38:39], v[200:201] op_sel_hi:[1,0,1]
	v_pk_fma_f32 v[44:45], v[150:151], v[38:39], v[202:203] op_sel_hi:[1,0,1]
	v_pk_fma_f32 v[46:47], v[152:153], v[38:39], v[190:191] op_sel_hi:[1,0,1]
	v_pk_fma_f32 v[48:49], v[154:155], v[38:39], v[192:193] op_sel_hi:[1,0,1]
	v_pk_fma_f32 v[50:51], v[156:157], v[38:39], v[194:195] op_sel_hi:[1,0,1]
	v_pk_fma_f32 v[0:1], v[158:159], v[38:39], v[0:1] op_sel_hi:[1,0,1]
	v_pk_mul_f32 v[160:161], v[2:3], v[36:37] op_sel_hi:[0,1]
	v_pk_mul_f32 v[190:191], v[2:3], v[40:41] op_sel_hi:[0,1]
	v_pk_mul_f32 v[192:193], v[2:3], v[42:43] op_sel_hi:[0,1]
	v_pk_mul_f32 v[194:195], v[2:3], v[44:45] op_sel_hi:[0,1]
	v_pk_mul_f32 v[196:197], v[2:3], v[46:47] op_sel_hi:[0,1]
	v_pk_mul_f32 v[198:199], v[2:3], v[48:49] op_sel_hi:[0,1]
	v_pk_mul_f32 v[200:201], v[2:3], v[50:51] op_sel_hi:[0,1]
	v_pk_mul_f32 v[0:1], v[2:3], v[0:1] op_sel_hi:[0,1]
	s_waitcnt lgkmcnt(0)
	ds_read_b128 v[36:39], v3 offset:5520
	ds_read_b128 v[40:43], v3 offset:5504
	ds_read_b128 v[44:47], v3 offset:5488
	ds_read_b128 v[48:51], v3 offset:5472
	ds_read_b128 v[52:55], v3 offset:4928
	ds_read_b128 v[144:147], v3 offset:4944
	ds_read_b128 v[148:151], v3 offset:4960
	ds_read_b128 v[152:155], v3 offset:4976
	ds_read_b32 v206, v142 offset:6016
	ds_read_b128 v[156:159], v128 offset:6144
	v_add_f32_dpp v167, v205, v205 row_half_mirror row_mask:0xf bank_mask:0xf bound_ctrl:1
	v_mul_f32_e32 v143, v162, v143
	v_fmac_f32_e32 v143, v2, v167
	v_cndmask_b32_e64 v143, v163, v143, s[52:53]
	v_pk_mul_f32 v[162:163], v[190:191], v[22:23]
	v_pk_mul_f32 v[18:19], v[190:191], v[18:19]
	v_pk_fma_f32 v[162:163], v[160:161], v[20:21], v[162:163]
	v_pk_fma_f32 v[16:17], v[160:161], v[16:17], v[18:19]
	v_pk_fma_f32 v[162:163], v[192:193], v[24:25], v[162:163]
	v_pk_fma_f32 v[12:13], v[192:193], v[12:13], v[16:17]
	v_pk_fma_f32 v[162:163], v[194:195], v[26:27], v[162:163]
	v_pk_fma_f32 v[12:13], v[194:195], v[14:15], v[12:13]
	v_pk_fma_f32 v[162:163], v[196:197], v[28:29], v[162:163]
	v_pk_fma_f32 v[8:9], v[196:197], v[8:9], v[12:13]
	v_pk_fma_f32 v[162:163], v[198:199], v[30:31], v[162:163]
	v_pk_fma_f32 v[8:9], v[198:199], v[10:11], v[8:9]
	v_pk_fma_f32 v[162:163], v[200:201], v[32:33], v[162:163]
	v_pk_fma_f32 v[4:5], v[200:201], v[4:5], v[8:9]
	v_pk_fma_f32 v[162:163], v[0:1], v[34:35], v[162:163]
	v_pk_fma_f32 v[4:5], v[0:1], v[6:7], v[4:5]
	v_add_f32_e32 v2, v162, v163
	v_add_f32_e32 v4, v4, v5
	v_rcp_f32_e32 v6, v164
	v_add_f32_dpp v2, v2, v2 quad_perm:[1,0,3,2] row_mask:0xf bank_mask:0xf bound_ctrl:1
	v_add_f32_dpp v4, v4, v4 quad_perm:[1,0,3,2] row_mask:0xf bank_mask:0xf bound_ctrl:1
	s_nop 0
	v_add_f32_dpp v2, v2, v2 quad_perm:[2,3,0,1] row_mask:0xf bank_mask:0xf bound_ctrl:1
	v_add_f32_dpp v4, v4, v4 quad_perm:[2,3,0,1] row_mask:0xf bank_mask:0xf bound_ctrl:1
	s_nop 0
	v_add_f32_dpp v2, v2, v2 row_half_mirror row_mask:0xf bank_mask:0xf bound_ctrl:1
	v_add_f32_dpp v4, v4, v4 row_half_mirror row_mask:0xf bank_mask:0xf bound_ctrl:1
	v_fma_f32 v5, -v164, v2, v204
	v_pk_mul_f32 v[202:203], v[164:165], v[4:5]
	v_mul_f32_e32 v2, v6, v203
	v_pk_fma_f32 v[204:205], v[20:21], v[2:3], v[160:161] op_sel_hi:[1,0,1]
	v_pk_fma_f32 v[190:191], v[22:23], v[2:3], v[190:191] op_sel_hi:[1,0,1]
	v_pk_fma_f32 v[192:193], v[24:25], v[2:3], v[192:193] op_sel_hi:[1,0,1]
	v_pk_fma_f32 v[194:195], v[26:27], v[2:3], v[194:195] op_sel_hi:[1,0,1]
	v_pk_fma_f32 v[196:197], v[28:29], v[2:3], v[196:197] op_sel_hi:[1,0,1]
	v_pk_fma_f32 v[198:199], v[30:31], v[2:3], v[198:199] op_sel_hi:[1,0,1]
	v_pk_fma_f32 v[200:201], v[32:33], v[2:3], v[200:201] op_sel_hi:[1,0,1]
	v_pk_fma_f32 v[0:1], v[34:35], v[2:3], v[0:1] op_sel_hi:[1,0,1]
	v_fmac_f32_e32 v202, v166, v203
	s_waitcnt lgkmcnt(0)
	ds_read_b128 v[4:7], v3 offset:6752
	ds_read_b128 v[8:11], v3 offset:6736
	ds_read_b128 v[12:15], v3 offset:6720
	ds_read_b128 v[16:19], v3 offset:6704
	ds_read_b128 v[20:23], v3 offset:6160
	ds_read_b128 v[24:27], v3 offset:6176
	ds_read_b128 v[28:31], v3 offset:6192
	ds_read_b128 v[32:35], v3 offset:6208
	ds_read_b32 v207, v142 offset:7248
	ds_read_b128 v[160:163], v128 offset:7376
	v_cndmask_b32_e64 v143, v143, v202, s[54:55]
	v_pk_mul_f32 v[166:167], v[190:191], v[54:55]
	v_pk_mul_f32 v[50:51], v[190:191], v[50:51]
	v_pk_fma_f32 v[166:167], v[204:205], v[52:53], v[166:167]
	v_pk_fma_f32 v[48:49], v[204:205], v[48:49], v[50:51]
	v_pk_fma_f32 v[166:167], v[192:193], v[144:145], v[166:167]
	v_pk_fma_f32 v[44:45], v[192:193], v[44:45], v[48:49]
	v_pk_fma_f32 v[166:167], v[194:195], v[146:147], v[166:167]
	v_pk_fma_f32 v[44:45], v[194:195], v[46:47], v[44:45]
	v_pk_fma_f32 v[166:167], v[196:197], v[148:149], v[166:167]
	v_pk_fma_f32 v[40:41], v[196:197], v[40:41], v[44:45]
	v_pk_fma_f32 v[166:167], v[198:199], v[150:151], v[166:167]
	v_mul_f32_e32 v164, v164, v156
	v_pk_fma_f32 v[166:167], v[200:201], v[152:153], v[166:167]
	v_pk_fma_f32 v[40:41], v[198:199], v[42:43], v[40:41]
	v_pk_fma_f32 v[166:167], v[0:1], v[154:155], v[166:167]
	v_pk_fma_f32 v[36:37], v[200:201], v[36:37], v[40:41]
	v_add_f32_e32 v2, v166, v167
	v_pk_fma_f32 v[36:37], v[0:1], v[38:39], v[36:37]
	s_nop 0
	v_add_f32_dpp v2, v2, v2 quad_perm:[1,0,3,2] row_mask:0xf bank_mask:0xf bound_ctrl:1
	v_add_f32_e32 v36, v36, v37
	v_mov_b32_e32 v37, v158
	v_add_f32_dpp v2, v2, v2 quad_perm:[2,3,0,1] row_mask:0xf bank_mask:0xf bound_ctrl:1
	v_add_f32_dpp v36, v36, v36 quad_perm:[1,0,3,2] row_mask:0xf bank_mask:0xf bound_ctrl:1
	s_nop 0
	v_add_f32_dpp v2, v2, v2 row_half_mirror row_mask:0xf bank_mask:0xf bound_ctrl:1
	v_fma_f32 v2, -v164, v2, v206
	v_mul_f32_e32 v165, v157, v2
	v_rcp_f32_e32 v2, v164
	v_add_f32_dpp v36, v36, v36 quad_perm:[2,3,0,1] row_mask:0xf bank_mask:0xf bound_ctrl:1
	v_mul_f32_e32 v2, v2, v165
	s_nop 0
	v_add_f32_dpp v36, v36, v36 row_half_mirror row_mask:0xf bank_mask:0xf bound_ctrl:1
	v_pk_fma_f32 v[166:167], v[52:53], v[2:3], v[204:205] op_sel_hi:[1,0,1]
	v_pk_fma_f32 v[190:191], v[54:55], v[2:3], v[190:191] op_sel_hi:[1,0,1]
	v_pk_fma_f32 v[192:193], v[144:145], v[2:3], v[192:193] op_sel_hi:[1,0,1]
	v_pk_fma_f32 v[194:195], v[146:147], v[2:3], v[194:195] op_sel_hi:[1,0,1]
	v_pk_fma_f32 v[196:197], v[148:149], v[2:3], v[196:197] op_sel_hi:[1,0,1]
	v_pk_fma_f32 v[198:199], v[150:151], v[2:3], v[198:199] op_sel_hi:[1,0,1]
	v_pk_fma_f32 v[200:201], v[152:153], v[2:3], v[200:201] op_sel_hi:[1,0,1]
	v_pk_fma_f32 v[0:1], v[154:155], v[2:3], v[0:1] op_sel_hi:[1,0,1]
	v_pk_mul_f32 v[36:37], v[36:37], v[164:165]
	s_waitcnt lgkmcnt(0)
; #define LBAR() do { asm volatile("s_waitcnt lgkmcnt(0)" ::: "memory"); __builtin_amdgcn_s_barrier(); asm volatile("" ::: "memory"); } while (0)
; #define LAS __attribute__((address_space(3)))
; #define GD_PIN(V) asm volatile("" : "+v"(V.k0), "+v"(V.k1), "+v"(V.k2), "+v"(V.k3), "+v"(V.q0), "+v"(V.q1), "+v"(V.q2), "+v"(V.q3), "+v"(V.vv), "+v"(V.abk), \
;     "+v"(S2[0]), "+v"(S2[1]), "+v"(S2[2]), "+v"(S2[3]), "+v"(S2[4]), "+v"(S2[5]), "+v"(S2[6]), "+v"(S2[7]))
; #define GD_2(jA, jB) GD_LDV(B, jA + 1); __builtin_amdgcn_sched_barrier(0); GD_STEP(A, jA); GD_PIN(B); \
;                      GD_LDV(A, jB + 1); __builtin_amdgcn_sched_barrier(0); GD_STEP(B, jB); GD_PIN(A);
; template <int NW>
; __device__ void scan_gdn(const P& p, int l, int b, int h, int dir, int part, LAS char* lds) {
;     ...
;   gd_load<TPW>(p, b, h, qc0, vc, dir, 0, wv, R);
;   GD_PREP(0);
;   gd_load<TPW>(p, b, h, qc0, vc, dir, 1, wv, R);
;   LBAR();
;   for (int g = 0; g < NCHK; ++g) {
;     LAS char* vbuf = lds + (g & 1) * TC * GD_VB;
;     LAS float* obuf = (LAS float*)(lds + GD_OFF_Y + (g & 1) * TC * NCOL * 4);
;     {
;       GdVec A, B;
;       LAS char* bk = vbuf + dq * 64 + (dq >> 2) * 16; LAS char* bv = vbuf + col * 4; LAS char* bc = vbuf;
;       GD_LDV(A, 0); GD_PIN(A);
; #pragma unroll 1
;       for (int s8 = 0; s8 < TC; s8 += 8) {
;         float ykeep = 0.f;
;         GD_2(0, 1) GD_2(2, 3) GD_2(4, 5) GD_2(6, 7)
;         obuf[(s8 + dq) * NCOL + col] = ykeep;
;         bk += 8 * GD_VB; bv += 8 * GD_VB; bc += 8 * GD_VB;
	v_add_f32_e32 v2, v36, v37
	ds_read_b32 v163, v142 offset:8480
	ds_read_b128 v[144:147], v3 offset:7984
	ds_read_b128 v[148:151], v3 offset:7968
	ds_read_b128 v[152:155], v3 offset:7952
	ds_read_b128 v[156:159], v3 offset:7936
	ds_read_b128 v[48:51], v3 offset:7392
	ds_read_b128 v[44:47], v3 offset:7408
	ds_read_b128 v[40:43], v3 offset:7424
	ds_read_b128 v[36:39], v3 offset:7440
	ds_read_b128 v[52:55], v128 offset:8608
	v_cndmask_b32_e64 v143, v143, v2, s[56:57]
	v_pk_mul_f32 v[202:203], v[190:191], v[22:23]
	v_pk_mul_f32 v[18:19], v[190:191], v[18:19]
	v_pk_fma_f32 v[202:203], v[166:167], v[20:21], v[202:203]
	v_pk_fma_f32 v[16:17], v[166:167], v[16:17], v[18:19]
	v_pk_fma_f32 v[202:203], v[192:193], v[24:25], v[202:203]
	v_pk_fma_f32 v[12:13], v[192:193], v[12:13], v[16:17]
	v_pk_fma_f32 v[202:203], v[194:195], v[26:27], v[202:203]
	v_pk_fma_f32 v[12:13], v[194:195], v[14:15], v[12:13]
	v_pk_fma_f32 v[202:203], v[196:197], v[28:29], v[202:203]
	v_pk_fma_f32 v[8:9], v[196:197], v[8:9], v[12:13]
	v_pk_fma_f32 v[202:203], v[198:199], v[30:31], v[202:203]
	v_pk_fma_f32 v[8:9], v[198:199], v[10:11], v[8:9]
	v_pk_fma_f32 v[202:203], v[200:201], v[32:33], v[202:203]
	v_pk_fma_f32 v[4:5], v[200:201], v[4:5], v[8:9]
	v_pk_fma_f32 v[202:203], v[0:1], v[34:35], v[202:203]
	v_pk_fma_f32 v[4:5], v[0:1], v[6:7], v[4:5]
	v_add_f32_e32 v2, v202, v203
	v_mul_f32_e32 v202, v164, v160
	v_add_f32_e32 v4, v4, v5
	v_add_f32_dpp v2, v2, v2 quad_perm:[1,0,3,2] row_mask:0xf bank_mask:0xf bound_ctrl:1
	v_rcp_f32_e32 v5, v202
	v_add_f32_dpp v4, v4, v4 quad_perm:[1,0,3,2] row_mask:0xf bank_mask:0xf bound_ctrl:1
	v_add_f32_dpp v2, v2, v2 quad_perm:[2,3,0,1] row_mask:0xf bank_mask:0xf bound_ctrl:1
	s_nop 0
	v_add_f32_dpp v203, v4, v4 quad_perm:[2,3,0,1] row_mask:0xf bank_mask:0xf bound_ctrl:1
	v_add_f32_dpp v2, v2, v2 row_half_mirror row_mask:0xf bank_mask:0xf bound_ctrl:1
	v_fma_f32 v2, -v202, v2, v207
	v_mul_f32_e32 v204, v161, v2
	v_mul_f32_e32 v2, v5, v204
	v_pk_fma_f32 v[160:161], v[20:21], v[2:3], v[166:167] op_sel_hi:[1,0,1]
	v_pk_fma_f32 v[164:165], v[22:23], v[2:3], v[190:191] op_sel_hi:[1,0,1]
	v_pk_fma_f32 v[166:167], v[24:25], v[2:3], v[192:193] op_sel_hi:[1,0,1]
	v_pk_fma_f32 v[190:191], v[26:27], v[2:3], v[194:195] op_sel_hi:[1,0,1]
	v_pk_fma_f32 v[192:193], v[28:29], v[2:3], v[196:197] op_sel_hi:[1,0,1]
	v_pk_fma_f32 v[194:195], v[30:31], v[2:3], v[198:199] op_sel_hi:[1,0,1]
	v_pk_fma_f32 v[196:197], v[32:33], v[2:3], v[200:201] op_sel_hi:[1,0,1]
	v_pk_fma_f32 v[198:199], v[34:35], v[2:3], v[0:1] op_sel_hi:[1,0,1]
	v_mul_f32_e32 v162, v162, v204
	s_waitcnt lgkmcnt(0)
	ds_read_b128 v[20:23], v3 offset:9216
	ds_read_b128 v[24:27], v3 offset:9200
	ds_read_b128 v[28:31], v3 offset:9184
	ds_read_b128 v[32:35], v3 offset:9168
	ds_read_b128 v[4:7], v3 offset:8624
	ds_read_b128 v[8:11], v3 offset:8640
	ds_read_b128 v[12:15], v3 offset:8656
	ds_read_b128 v[16:19], v3 offset:8672
	ds_read_b32 v55, v142 offset:9712
	ds_read_b128 v[0:3], v128 offset:9840
	v_add_f32_dpp v142, v203, v203 row_half_mirror row_mask:0xf bank_mask:0xf bound_ctrl:1
	v_fmac_f32_e32 v162, v202, v142
	v_cndmask_b32_e64 v162, v143, v162, s[58:59]
	v_pk_mul_f32 v[142:143], v[164:165], v[50:51]
	v_pk_mul_f32 v[158:159], v[164:165], v[158:159]
	v_pk_fma_f32 v[142:143], v[160:161], v[48:49], v[142:143]
	v_pk_fma_f32 v[156:157], v[160:161], v[156:157], v[158:159]
	v_pk_fma_f32 v[142:143], v[166:167], v[44:45], v[142:143]
	v_pk_fma_f32 v[152:153], v[166:167], v[152:153], v[156:157]
	v_pk_fma_f32 v[142:143], v[190:191], v[46:47], v[142:143]
	v_pk_fma_f32 v[152:153], v[190:191], v[154:155], v[152:153]
	v_pk_fma_f32 v[142:143], v[192:193], v[40:41], v[142:143]
	v_pk_fma_f32 v[148:149], v[192:193], v[148:149], v[152:153]
	v_pk_fma_f32 v[142:143], v[194:195], v[42:43], v[142:143]
	v_mul_f32_e32 v52, v202, v52
	v_pk_fma_f32 v[142:143], v[196:197], v[36:37], v[142:143]
	v_pk_fma_f32 v[148:149], v[194:195], v[150:151], v[148:149]
	v_pk_fma_f32 v[142:143], v[198:199], v[38:39], v[142:143]
	v_pk_fma_f32 v[144:145], v[196:197], v[144:145], v[148:149]
	v_add_f32_e32 v142, v142, v143
	v_pk_fma_f32 v[144:145], v[198:199], v[146:147], v[144:145]
	s_add_i32 s30, s30, 8
	v_add_f32_dpp v142, v142, v142 quad_perm:[1,0,3,2] row_mask:0xf bank_mask:0xf bound_ctrl:1
	v_add_f32_e32 v143, v144, v145
	v_add_u32_e32 v128, 0x2680, v128
	v_add_f32_dpp v142, v142, v142 quad_perm:[2,3,0,1] row_mask:0xf bank_mask:0xf bound_ctrl:1
	v_add_f32_dpp v143, v143, v143 quad_perm:[1,0,3,2] row_mask:0xf bank_mask:0xf bound_ctrl:1
	s_cmp_gt_u32 s30, 23
	v_add_f32_dpp v142, v142, v142 row_half_mirror row_mask:0xf bank_mask:0xf bound_ctrl:1
	v_fma_f32 v142, -v52, v142, v163
	v_mul_f32_e32 v53, v53, v142
	v_rcp_f32_e32 v142, v52
	v_add_f32_dpp v143, v143, v143 quad_perm:[2,3,0,1] row_mask:0xf bank_mask:0xf bound_ctrl:1
	v_mul_f32_e32 v142, v142, v53
	s_nop 0
	v_add_f32_dpp v150, v143, v143 row_half_mirror row_mask:0xf bank_mask:0xf bound_ctrl:1
	v_pk_fma_f32 v[48:49], v[48:49], v[142:143], v[160:161] op_sel_hi:[1,0,1]
	v_pk_fma_f32 v[144:145], v[50:51], v[142:143], v[164:165] op_sel_hi:[1,0,1]
	v_pk_fma_f32 v[44:45], v[44:45], v[142:143], v[166:167] op_sel_hi:[1,0,1]
	v_pk_fma_f32 v[146:147], v[46:47], v[142:143], v[190:191] op_sel_hi:[1,0,1]
	v_pk_fma_f32 v[40:41], v[40:41], v[142:143], v[192:193] op_sel_hi:[1,0,1]
	v_pk_fma_f32 v[148:149], v[42:43], v[142:143], v[194:195] op_sel_hi:[1,0,1]
	v_pk_fma_f32 v[36:37], v[36:37], v[142:143], v[196:197] op_sel_hi:[1,0,1]
	v_pk_fma_f32 v[142:143], v[38:39], v[142:143], v[198:199] op_sel_hi:[1,0,1]
	v_mul_f32_e32 v38, v54, v53
	v_fmac_f32_e32 v38, v52, v150
	v_cndmask_b32_e64 v53, v162, v38, s[60:61]
	v_pk_mul_f32 v[50:51], v[52:53], v[48:49] op_sel_hi:[0,1]
	v_pk_mul_f32 v[48:49], v[52:53], v[144:145] op_sel_hi:[0,1]
	v_pk_mul_f32 v[46:47], v[52:53], v[44:45] op_sel_hi:[0,1]
	v_pk_mul_f32 v[44:45], v[52:53], v[146:147] op_sel_hi:[0,1]
	v_pk_mul_f32 v[42:43], v[52:53], v[40:41] op_sel_hi:[0,1]
	v_pk_mul_f32 v[40:41], v[52:53], v[148:149] op_sel_hi:[0,1]
	v_pk_mul_f32 v[38:39], v[52:53], v[36:37] op_sel_hi:[0,1]
	v_pk_mul_f32 v[36:37], v[52:53], v[142:143] op_sel_hi:[0,1]
	s_waitcnt lgkmcnt(0)
	v_add_u32_e32 v3, v141, v100
	v_add_u32_e32 v141, 0x400, v141
	ds_write_b32 v3, v53
	s_cbranch_scc0 .LBB0_245
; template <int NW>
; __device__ void scan_gdn(const P& p, int l, int b, int h, int dir, int part, LAS char* lds) {
;     ...
;     if (g + 1 < NCHK) GD_PREP(g + 1);
	s_add_i32 s30, s26, 1
	s_cmpk_lg_i32 s26, 0x87
	s_cbranch_scc0 .LBB0_280
	s_lshl_b32 s20, s30, 5
	s_and_b32 s20, s20, 32
	s_mulk_i32 s20, 0x4d0
	s_waitcnt vmcnt(0)
	v_lshlrev_b32_e32 v3, 16, v81
	v_lshlrev_b32_e32 v4, 16, v82
	v_add_u32_e32 v0, s20, v78
	v_lshlrev_b32_e32 v1, 16, v79
	v_lshlrev_b32_e32 v2, 16, v80
	ds_write2_b32 v0, v3, v4 offset1:68
	ds_write2_b32 v0, v1, v2 offset0:136 offset1:204
	v_lshlrev_b32_e32 v3, 16, v87
	v_lshlrev_b32_e32 v4, 16, v88
	v_add_u32_e32 v5, 0x400, v0
	v_lshlrev_b32_e32 v1, 16, v85
	v_lshlrev_b32_e32 v2, 16, v86
	ds_write2_b32 v5, v3, v4 offset0:52 offset1:120
	v_add_u32_e32 v3, 0x600, v0
	ds_write2_b32 v3, v1, v2 offset0:60 offset1:128
	v_lshlrev_b32_e32 v3, 16, v93
	v_lshlrev_b32_e32 v4, 16, v94
	v_add_u32_e32 v5, 0x800, v0
	v_lshlrev_b32_e32 v1, 16, v91
	v_lshlrev_b32_e32 v2, 16, v92
	ds_write2_b32 v5, v3, v4 offset0:104 offset1:172
	v_add_u32_e32 v3, 0xa00, v0
	ds_write2_b32 v3, v1, v2 offset0:112 offset1:180
	v_lshlrev_b32_e32 v3, 16, v107
	v_lshlrev_b32_e32 v4, 16, v108
	v_add_u32_e32 v5, 0xc00, v0
	v_lshlrev_b32_e32 v1, 16, v103
	v_lshlrev_b32_e32 v2, 16, v105
	ds_write2_b32 v5, v3, v4 offset0:156 offset1:224
	v_add_u32_e32 v3, 0x1000, v0
	ds_write2_b32 v3, v1, v2 offset0:36 offset1:104
	v_lshlrev_b32_e32 v3, 16, v115
	v_lshlrev_b32_e32 v4, 16, v116
	v_add_u32_e32 v5, 0x1200, v0
	v_lshlrev_b32_e32 v1, 16, v113
	v_lshlrev_b32_e32 v2, 16, v114
	ds_write2_b32 v5, v3, v4 offset0:80 offset1:148
	v_add_u32_e32 v3, 0x1400, v0
	ds_write2_b32 v3, v1, v2 offset0:88 offset1:156
	v_lshlrev_b32_e32 v3, 16, v121
	v_lshlrev_b32_e32 v4, 16, v122
	v_add_u32_e32 v5, 0x1800, v0
	v_lshlrev_b32_e32 v1, 16, v119
	v_lshlrev_b32_e32 v2, 16, v120
	ds_write2_b32 v5, v3, v4 offset0:4 offset1:72
	ds_write2_b32 v5, v1, v2 offset0:140 offset1:208
	v_lshlrev_b32_e32 v3, 16, v127
	v_lshlrev_b32_e32 v4, 16, v134
	v_add_u32_e32 v5, 0x1c00, v0
	v_lshlrev_b32_e32 v1, 16, v125
	v_lshlrev_b32_e32 v2, 16, v126
	ds_write2_b32 v5, v3, v4 offset0:56 offset1:124
	v_add_u32_e32 v3, 0x1e00, v0
	ds_write2_b32 v3, v1, v2 offset0:64 offset1:132
	v_lshlrev_b32_e32 v3, 16, v138
	v_lshlrev_b32_e32 v4, 16, v139
	v_add_u32_e32 v5, 0x2000, v0
	v_lshlrev_b32_e32 v1, 16, v57
	v_lshlrev_b32_e32 v2, 16, v137
	ds_write2_b32 v5, v3, v4 offset0:108 offset1:176
	v_add_u32_e32 v3, 0x2200, v0
	ds_write2_b32 v3, v1, v2 offset0:116 offset1:184
	s_and_saveexec_b64 s[36:37], s[38:39]
	v_lshlrev_b32_e32 v1, 16, v83
	ds_write_b32 v0, v1 offset:1088
	v_lshlrev_b32_e32 v1, 16, v89
	ds_write_b32 v0, v1 offset:2320
	v_lshlrev_b32_e32 v1, 16, v95
	ds_write_b32 v0, v1 offset:3552
	v_lshlrev_b32_e32 v1, 16, v111
	ds_write_b32 v0, v1 offset:4784
	v_lshlrev_b32_e32 v1, 16, v117
	ds_write_b32 v0, v1 offset:6016
	v_lshlrev_b32_e32 v1, 16, v123
	ds_write_b32 v0, v1 offset:7248
	v_lshlrev_b32_e32 v1, 16, v135
	ds_write_b32 v0, v1 offset:8480
	v_lshlrev_b32_e32 v1, 16, v59
	ds_write_b32 v0, v1 offset:9712
	s_or_b64 exec, exec, s[36:37]
	s_and_saveexec_b64 s[36:37], s[40:41]
	v_cndmask_b32_e64 v1, v84, v61, s[44:45]
	v_cndmask_b32_e64 v1, v1, v60, s[42:43]
	ds_write_b32 v0, v1 offset:1216
	v_cndmask_b32_e64 v1, v90, v63, s[44:45]
	v_cndmask_b32_e64 v1, v1, v62, s[42:43]
	ds_write_b32 v0, v1 offset:2448
	v_cndmask_b32_e64 v1, v96, v65, s[44:45]
	v_cndmask_b32_e64 v1, v1, v64, s[42:43]
	ds_write_b32 v0, v1 offset:3680
	v_cndmask_b32_e64 v1, v112, v67, s[44:45]
	v_cndmask_b32_e64 v1, v1, v66, s[42:43]
	ds_write_b32 v0, v1 offset:4912
	v_cndmask_b32_e64 v1, v118, v69, s[44:45]
	v_cndmask_b32_e64 v1, v1, v68, s[42:43]
	ds_write_b32 v0, v1 offset:6144
	v_cndmask_b32_e64 v1, v124, v71, s[44:45]
	v_cndmask_b32_e64 v1, v1, v70, s[42:43]
	ds_write_b32 v0, v1 offset:7376
	v_cndmask_b32_e64 v1, v136, v73, s[44:45]
	v_cndmask_b32_e64 v1, v1, v72, s[42:43]
	ds_write_b32 v0, v1 offset:8608
	v_cndmask_b32_e64 v1, v140, v75, s[44:45]
	v_cndmask_b32_e64 v1, v1, v74, s[42:43]
	ds_write_b32 v0, v1 offset:9840
	s_or_b64 exec, exec, s[36:37]
